# v19: v18 + P11 LN2 row loop with four rows in flight, valid rows enumerated without the held-back range
# baseline (speedup 1.0000x reference)
; DI float bflo(unsigned w) { return __uint_as_float(w << 16); }
; DI float bfhi(unsigned w) { return __uint_as_float(w & 0xffff0000u); }
; template <bool F32OUT> DI void ln_row_bf16(const bf16_t* z, const float* w, const float* bb, void* o, int lane) {
;     float v[16]; float s = 0.f;
; #pragma unroll
;     for (int j = 0; j < 2; ++j) { const u32x4 p = *(const u32x4*)(z + 512 * j + 8 * lane);
;         v[8 * j + 0] = bflo(p.x); v[8 * j + 1] = bfhi(p.x); v[8 * j + 2] = bflo(p.y); v[8 * j + 3] = bfhi(p.y); v[8 * j + 4] = bflo(p.z); v[8 * j + 5] = bfhi(p.z); v[8 * j + 6] = bflo(p.w); v[8 * j + 7] = bfhi(p.w); }
; #pragma unroll
;     for (int i = 0; i < 16; ++i) s += v[i];
;     const float mean = wave_sum(s) * (1.f / 1024.f); float s2 = 0.f;
; #pragma unroll
;     for (int i = 0; i < 16; ++i) { v[i] -= mean; s2 += v[i] * v[i]; }
;     const float rstd = __builtin_amdgcn_rsqf(wave_sum(s2) * (1.f / 1024.f) + 1e-5f);
; __global__ void __launch_bounds__(512, 2) fwd_kernel(Params P) {
;     ...
;         else { for (int m = (cu - 32) * 8 + wave; m < MP; m += (G - 32) * 8) if (m < 7808 || m >= 9216) ln_row_bf16<true>(PROJ + (size_t)m * NPJ + C_Z, P.in[I_LN2W], P.in[I_LN2B], P.out + O_YP + (size_t)m * 1024, lane); }
.LBB0_1683:
	s_cmp_lt_i32 s90, 12
	s_cselect_b64 s[6:7], -1, 0
	s_add_u32 s4, s48, 0x1bcc4000
	s_addc_u32 s5, s49, 0
	s_and_b64 s[6:7], s[6:7], s[8:9]
	s_andn2_b64 vcc, exec, s[6:7]
	s_cbranch_vccnz .LBB0_1699
	s_cmp_gt_i32 s2, 31
	s_mov_b64 s[8:9], -1
	s_cbranch_scc0 .LBB0_1691
	s_add_i32 s8, s44, 0xffffff00
	s_cmpk_gt_i32 s8, 0x7fff
	s_cbranch_scc1 .LBB0_1690
	s_load_dwordx4 s[60:63], s[0:1], 0xb8
	v_lshlrev_b32_e32 v6, 5, v182
	v_lshlrev_b32_e32 v220, 4, v182
	v_mov_b32_e32 v13, 0x3727c5ac
	s_waitcnt lgkmcnt(0)
	global_load_dwordx4 v[130:133], v6, s[60:61]
	global_load_dwordx4 v[134:137], v6, s[60:61] offset:16
	global_load_dwordx4 v[138:141], v6, s[60:61] offset:2048
	global_load_dwordx4 v[142:145], v6, s[60:61] offset:2064
	global_load_dwordx4 v[146:149], v6, s[62:63]
	global_load_dwordx4 v[150:153], v6, s[62:63] offset:16
	global_load_dwordx4 v[154:157], v6, s[62:63] offset:2048
	global_load_dwordx4 v[158:161], v6, s[62:63] offset:2064
	s_add_i32 s31, s46, 0xffffff00
	s_mov_b32 s26, s8
	s_add_i32 s27, s26, s31
	s_add_i32 s28, s27, s31
	s_add_i32 s29, s28, s31
	s_lshl_b32 s31, s31, 2
	s_min_i32 s32, s26, 0x7a7f
	s_add_i32 s33, s32, 0x580
	s_cmp_lt_i32 s32, 0x1e80
	s_cselect_b32 s33, s32, s33
	s_mul_hi_i32 s35, s33, 0x3200
	s_mul_i32 s34, s33, 0x3200
	s_add_u32 s34, s48, s34
	s_addc_u32 s35, s49, s35
	global_load_dwordx4 v[162:165], v220, s[34:35]
	global_load_dwordx4 v[166:169], v220, s[34:35] offset:1024
	s_min_i32 s32, s27, 0x7a7f
	s_add_i32 s33, s32, 0x580
	s_cmp_lt_i32 s32, 0x1e80
	s_cselect_b32 s33, s32, s33
	s_mul_hi_i32 s35, s33, 0x3200
	s_mul_i32 s34, s33, 0x3200
	s_add_u32 s34, s48, s34
	s_addc_u32 s35, s49, s35
	global_load_dwordx4 v[170:173], v220, s[34:35]
	global_load_dwordx4 v[174:177], v220, s[34:35] offset:1024
	s_min_i32 s32, s28, 0x7a7f
	s_add_i32 s33, s32, 0x580
	s_cmp_lt_i32 s32, 0x1e80
	s_cselect_b32 s33, s32, s33
	s_mul_hi_i32 s35, s33, 0x3200
	s_mul_i32 s34, s33, 0x3200
	s_add_u32 s34, s48, s34
	s_addc_u32 s35, s49, s35
	global_load_dwordx4 v[222:225], v220, s[34:35]
	global_load_dwordx4 v[226:229], v220, s[34:35] offset:1024
	s_min_i32 s32, s29, 0x7a7f
	s_add_i32 s33, s32, 0x580
	s_cmp_lt_i32 s32, 0x1e80
	s_cselect_b32 s33, s32, s33
	s_mul_hi_i32 s35, s33, 0x3200
	s_mul_i32 s34, s33, 0x3200
	s_add_u32 s34, s48, s34
	s_addc_u32 s35, s49, s35
	global_load_dwordx4 v[230:233], v220, s[34:35]
	global_load_dwordx4 v[234:237], v220, s[34:35] offset:1024
	s_waitcnt vmcnt(0)
.Lp11ln_loop:
	s_cmp_gt_i32 s26, 0x7a7f
	s_cbranch_scc1 .Lp11ln_done
	s_waitcnt vmcnt(18)
	v_lshlrev_b32_e32 v184, 16, v162
	v_and_b32_e32 v185, 0xffff0000, v162
	v_lshlrev_b32_e32 v186, 16, v163
	v_and_b32_e32 v187, 0xffff0000, v163
	v_lshlrev_b32_e32 v188, 16, v164
	v_and_b32_e32 v189, 0xffff0000, v164
	v_lshlrev_b32_e32 v190, 16, v165
	v_and_b32_e32 v191, 0xffff0000, v165
	v_lshlrev_b32_e32 v192, 16, v166
	v_and_b32_e32 v193, 0xffff0000, v166
	v_lshlrev_b32_e32 v194, 16, v167
	v_and_b32_e32 v195, 0xffff0000, v167
	v_lshlrev_b32_e32 v196, 16, v168
	v_and_b32_e32 v197, 0xffff0000, v168
	v_lshlrev_b32_e32 v198, 16, v169
	v_and_b32_e32 v199, 0xffff0000, v169
	v_pk_add_f32 v[200:201], v[184:185], v[186:187]
	v_pk_add_f32 v[202:203], v[188:189], v[190:191]
	v_pk_add_f32 v[204:205], v[192:193], v[194:195]
	v_pk_add_f32 v[206:207], v[196:197], v[198:199]
	v_pk_add_f32 v[200:201], v[200:201], v[202:203]
	v_pk_add_f32 v[204:205], v[204:205], v[206:207]
	v_pk_add_f32 v[200:201], v[200:201], v[204:205]
	s_nop 0
	v_add_f32_e32 v208, v200, v201
	s_nop 1
	v_add_f32_dpp v208, v208, v208 quad_perm:[1,0,3,2] row_mask:0xf bank_mask:0xf
	s_nop 1
	v_add_f32_dpp v208, v208, v208 quad_perm:[2,3,0,1] row_mask:0xf bank_mask:0xf
	s_nop 1
	v_add_f32_dpp v208, v208, v208 row_half_mirror row_mask:0xf bank_mask:0xf
	s_nop 1
	v_add_f32_dpp v208, v208, v208 row_mirror row_mask:0xf bank_mask:0xf
	s_nop 1
	v_add_f32_dpp v208, v208, v208 row_bcast:15 row_mask:0xa bank_mask:0xf
	s_nop 1
	v_add_f32_dpp v208, v208, v208 row_bcast:31 row_mask:0xc bank_mask:0xf
	s_nop 1
	v_readlane_b32 s30, v208, 63
	s_nop 1
	v_mov_b32_e32 v210, s30
	v_mul_f32_e32 v210, 0xba800000, v210
	v_pk_add_f32 v[184:185], v[184:185], v[210:211] op_sel_hi:[1,0]
	v_pk_add_f32 v[186:187], v[186:187], v[210:211] op_sel_hi:[1,0]
	v_pk_add_f32 v[188:189], v[188:189], v[210:211] op_sel_hi:[1,0]
	v_pk_add_f32 v[190:191], v[190:191], v[210:211] op_sel_hi:[1,0]
	v_pk_add_f32 v[192:193], v[192:193], v[210:211] op_sel_hi:[1,0]
	v_pk_add_f32 v[194:195], v[194:195], v[210:211] op_sel_hi:[1,0]
	v_pk_add_f32 v[196:197], v[196:197], v[210:211] op_sel_hi:[1,0]
	v_pk_add_f32 v[198:199], v[198:199], v[210:211] op_sel_hi:[1,0]
	v_pk_mul_f32 v[200:201], v[184:185], v[184:185]
	v_pk_mul_f32 v[202:203], v[192:193], v[192:193]
	v_pk_fma_f32 v[200:201], v[186:187], v[186:187], v[200:201]
	v_pk_fma_f32 v[202:203], v[194:195], v[194:195], v[202:203]
	v_pk_fma_f32 v[200:201], v[188:189], v[188:189], v[200:201]
	v_pk_fma_f32 v[202:203], v[196:197], v[196:197], v[202:203]
	v_pk_fma_f32 v[200:201], v[190:191], v[190:191], v[200:201]
	v_pk_fma_f32 v[202:203], v[198:199], v[198:199], v[202:203]
	v_pk_add_f32 v[200:201], v[200:201], v[202:203]
	s_nop 0
	v_add_f32_e32 v208, v200, v201
	s_nop 1
	v_add_f32_dpp v208, v208, v208 quad_perm:[1,0,3,2] row_mask:0xf bank_mask:0xf
	s_nop 1
	v_add_f32_dpp v208, v208, v208 quad_perm:[2,3,0,1] row_mask:0xf bank_mask:0xf
	s_nop 1
	v_add_f32_dpp v208, v208, v208 row_half_mirror row_mask:0xf bank_mask:0xf
	s_nop 1
	v_add_f32_dpp v208, v208, v208 row_mirror row_mask:0xf bank_mask:0xf
	s_nop 1
	v_add_f32_dpp v208, v208, v208 row_bcast:15 row_mask:0xa bank_mask:0xf
	s_nop 1
	v_add_f32_dpp v208, v208, v208 row_bcast:31 row_mask:0xc bank_mask:0xf
; DI u32x4 pack8(f32x4 a, f32x4 b) { u32x4 w; w.x = pk2(a[0], a[1]); w.y = pk2(a[2], a[3]); w.z = pk2(b[0], b[1]); w.w = pk2(b[2], b[3]); return w; }
; template <bool F32OUT> DI void ln_row_bf16(const bf16_t* z, const float* w, const float* bb, void* o, int lane) {
;     ...
;     const float rstd = __builtin_amdgcn_rsqf(wave_sum(s2) * (1.f / 1024.f) + 1e-5f);
; #pragma unroll
;     for (int j = 0; j < 2; ++j) { const int c = 512 * j + 8 * lane; const f32x4 w0 = *(const f32x4*)(w + c), w1 = *(const f32x4*)(w + c + 4), b0 = *(const f32x4*)(bb + c), b1 = *(const f32x4*)(bb + c + 4);
;         f32x4 y0, y1;
; #pragma unroll
;         for (int i = 0; i < 4; ++i) { y0[i] = v[8 * j + i] * rstd * w0[i] + b0[i]; y1[i] = v[8 * j + 4 + i] * rstd * w1[i] + b1[i]; }
;         if (F32OUT) { *(f32x4*)((float*)o + c) = y0; *(f32x4*)((float*)o + c + 4) = y1; }
;         else *(u32x4*)((bf16_t*)o + c) = pack8(y0, y1); }
; __global__ void __launch_bounds__(512, 2) fwd_kernel(Params P) {
;     ...
;         else { for (int m = (cu - 32) * 8 + wave; m < MP; m += (G - 32) * 8) if (m < 7808 || m >= 9216) ln_row_bf16<true>(PROJ + (size_t)m * NPJ + C_Z, P.in[I_LN2W], P.in[I_LN2B], P.out + O_YP + (size_t)m * 1024, lane); }
	s_nop 1
	v_readlane_b32 s30, v208, 63
	s_nop 1
	v_mov_b32_e32 v210, s30
	v_fmamk_f32 v210, v210, 0x3a800000, v13
	v_rsq_f32_e32 v210, v210
	s_add_i32 s33, s26, 0x580
	s_cmp_lt_i32 s26, 0x1e80
	s_cselect_b32 s33, s26, s33
	s_mov_b32 s36, s33
	s_mov_b32 s37, 0
	s_lshl_b64 s[36:37], s[36:37], 12
	s_add_u32 s36, s42, s36
	s_addc_u32 s37, s43, s37
	v_pk_mul_f32 v[184:185], v[184:185], v[210:211] op_sel_hi:[1,0]
	v_pk_mul_f32 v[186:187], v[186:187], v[210:211] op_sel_hi:[1,0]
	v_pk_mul_f32 v[188:189], v[188:189], v[210:211] op_sel_hi:[1,0]
	v_pk_mul_f32 v[190:191], v[190:191], v[210:211] op_sel_hi:[1,0]
	v_pk_mul_f32 v[192:193], v[192:193], v[210:211] op_sel_hi:[1,0]
	v_pk_mul_f32 v[194:195], v[194:195], v[210:211] op_sel_hi:[1,0]
	v_pk_mul_f32 v[196:197], v[196:197], v[210:211] op_sel_hi:[1,0]
	v_pk_mul_f32 v[198:199], v[198:199], v[210:211] op_sel_hi:[1,0]
	v_pk_fma_f32 v[200:201], v[130:131], v[184:185], v[146:147]
	v_pk_fma_f32 v[202:203], v[132:133], v[186:187], v[148:149]
	v_pk_fma_f32 v[204:205], v[134:135], v[188:189], v[150:151]
	v_pk_fma_f32 v[206:207], v[136:137], v[190:191], v[152:153]
	global_store_dwordx4 v6, v[200:203], s[36:37]
	global_store_dwordx4 v6, v[204:207], s[36:37] offset:16
	v_pk_fma_f32 v[212:213], v[138:139], v[192:193], v[154:155]
	v_pk_fma_f32 v[214:215], v[140:141], v[194:195], v[156:157]
	v_pk_fma_f32 v[216:217], v[142:143], v[196:197], v[158:159]
	v_pk_fma_f32 v[218:219], v[144:145], v[198:199], v[160:161]
	global_store_dwordx4 v6, v[212:215], s[36:37] offset:2048
	global_store_dwordx4 v6, v[216:219], s[36:37] offset:2064
	s_add_i32 s26, s26, s31
	s_min_i32 s32, s26, 0x7a7f
	s_add_i32 s33, s32, 0x580
	s_cmp_lt_i32 s32, 0x1e80
	s_cselect_b32 s33, s32, s33
	s_mul_hi_i32 s35, s33, 0x3200
	s_mul_i32 s34, s33, 0x3200
	s_add_u32 s34, s48, s34
	s_addc_u32 s35, s49, s35
	global_load_dwordx4 v[162:165], v220, s[34:35]
	global_load_dwordx4 v[166:169], v220, s[34:35] offset:1024
	s_cmp_gt_i32 s27, 0x7a7f
	s_cbranch_scc1 .Lp11ln_done
	s_waitcnt vmcnt(18)
	v_lshlrev_b32_e32 v184, 16, v170
	v_and_b32_e32 v185, 0xffff0000, v170
	v_lshlrev_b32_e32 v186, 16, v171
	v_and_b32_e32 v187, 0xffff0000, v171
	v_lshlrev_b32_e32 v188, 16, v172
	v_and_b32_e32 v189, 0xffff0000, v172
	v_lshlrev_b32_e32 v190, 16, v173
	v_and_b32_e32 v191, 0xffff0000, v173
	v_lshlrev_b32_e32 v192, 16, v174
	v_and_b32_e32 v193, 0xffff0000, v174
	v_lshlrev_b32_e32 v194, 16, v175
	v_and_b32_e32 v195, 0xffff0000, v175
	v_lshlrev_b32_e32 v196, 16, v176
	v_and_b32_e32 v197, 0xffff0000, v176
	v_lshlrev_b32_e32 v198, 16, v177
	v_and_b32_e32 v199, 0xffff0000, v177
	v_pk_add_f32 v[200:201], v[184:185], v[186:187]
	v_pk_add_f32 v[202:203], v[188:189], v[190:191]
	v_pk_add_f32 v[204:205], v[192:193], v[194:195]
	v_pk_add_f32 v[206:207], v[196:197], v[198:199]
	v_pk_add_f32 v[200:201], v[200:201], v[202:203]
	v_pk_add_f32 v[204:205], v[204:205], v[206:207]
	v_pk_add_f32 v[200:201], v[200:201], v[204:205]
	s_nop 0
	v_add_f32_e32 v208, v200, v201
	s_nop 1
	v_add_f32_dpp v208, v208, v208 quad_perm:[1,0,3,2] row_mask:0xf bank_mask:0xf
	s_nop 1
	v_add_f32_dpp v208, v208, v208 quad_perm:[2,3,0,1] row_mask:0xf bank_mask:0xf
	s_nop 1
	v_add_f32_dpp v208, v208, v208 row_half_mirror row_mask:0xf bank_mask:0xf
	s_nop 1
	v_add_f32_dpp v208, v208, v208 row_mirror row_mask:0xf bank_mask:0xf
	s_nop 1
	v_add_f32_dpp v208, v208, v208 row_bcast:15 row_mask:0xa bank_mask:0xf
	s_nop 1
	v_add_f32_dpp v208, v208, v208 row_bcast:31 row_mask:0xc bank_mask:0xf
	s_nop 1
	v_readlane_b32 s30, v208, 63
	s_nop 1
	v_mov_b32_e32 v210, s30
	v_mul_f32_e32 v210, 0xba800000, v210
	v_pk_add_f32 v[184:185], v[184:185], v[210:211] op_sel_hi:[1,0]
	v_pk_add_f32 v[186:187], v[186:187], v[210:211] op_sel_hi:[1,0]
	v_pk_add_f32 v[188:189], v[188:189], v[210:211] op_sel_hi:[1,0]
	v_pk_add_f32 v[190:191], v[190:191], v[210:211] op_sel_hi:[1,0]
	v_pk_add_f32 v[192:193], v[192:193], v[210:211] op_sel_hi:[1,0]
	v_pk_add_f32 v[194:195], v[194:195], v[210:211] op_sel_hi:[1,0]
	v_pk_add_f32 v[196:197], v[196:197], v[210:211] op_sel_hi:[1,0]
	v_pk_add_f32 v[198:199], v[198:199], v[210:211] op_sel_hi:[1,0]
	v_pk_mul_f32 v[200:201], v[184:185], v[184:185]
	v_pk_mul_f32 v[202:203], v[192:193], v[192:193]
	v_pk_fma_f32 v[200:201], v[186:187], v[186:187], v[200:201]
	v_pk_fma_f32 v[202:203], v[194:195], v[194:195], v[202:203]
	v_pk_fma_f32 v[200:201], v[188:189], v[188:189], v[200:201]
	v_pk_fma_f32 v[202:203], v[196:197], v[196:197], v[202:203]
	v_pk_fma_f32 v[200:201], v[190:191], v[190:191], v[200:201]
	v_pk_fma_f32 v[202:203], v[198:199], v[198:199], v[202:203]
	v_pk_add_f32 v[200:201], v[200:201], v[202:203]
	s_nop 0
	v_add_f32_e32 v208, v200, v201
	s_nop 1
	v_add_f32_dpp v208, v208, v208 quad_perm:[1,0,3,2] row_mask:0xf bank_mask:0xf
	s_nop 1
	v_add_f32_dpp v208, v208, v208 quad_perm:[2,3,0,1] row_mask:0xf bank_mask:0xf
	s_nop 1
	v_add_f32_dpp v208, v208, v208 row_half_mirror row_mask:0xf bank_mask:0xf
	s_nop 1
	v_add_f32_dpp v208, v208, v208 row_mirror row_mask:0xf bank_mask:0xf
	s_nop 1
	v_add_f32_dpp v208, v208, v208 row_bcast:15 row_mask:0xa bank_mask:0xf
	s_nop 1
	v_add_f32_dpp v208, v208, v208 row_bcast:31 row_mask:0xc bank_mask:0xf
	s_nop 1
	v_readlane_b32 s30, v208, 63
	s_nop 1
	v_mov_b32_e32 v210, s30
	v_fmamk_f32 v210, v210, 0x3a800000, v13
	v_rsq_f32_e32 v210, v210
	s_add_i32 s33, s27, 0x580
	s_cmp_lt_i32 s27, 0x1e80
	s_cselect_b32 s33, s27, s33
	s_mov_b32 s36, s33
	s_mov_b32 s37, 0
	s_lshl_b64 s[36:37], s[36:37], 12
	s_add_u32 s36, s42, s36
	s_addc_u32 s37, s43, s37
	v_pk_mul_f32 v[184:185], v[184:185], v[210:211] op_sel_hi:[1,0]
	v_pk_mul_f32 v[186:187], v[186:187], v[210:211] op_sel_hi:[1,0]
; DI float bflo(unsigned w) { return __uint_as_float(w << 16); }
; DI float bfhi(unsigned w) { return __uint_as_float(w & 0xffff0000u); }
; DI u32x4 pack8(f32x4 a, f32x4 b) { u32x4 w; w.x = pk2(a[0], a[1]); w.y = pk2(a[2], a[3]); w.z = pk2(b[0], b[1]); w.w = pk2(b[2], b[3]); return w; }
; template <bool F32OUT> DI void ln_row_bf16(const bf16_t* z, const float* w, const float* bb, void* o, int lane) {
;     float v[16]; float s = 0.f;
; #pragma unroll
;     for (int j = 0; j < 2; ++j) { const u32x4 p = *(const u32x4*)(z + 512 * j + 8 * lane);
;         v[8 * j + 0] = bflo(p.x); v[8 * j + 1] = bfhi(p.x); v[8 * j + 2] = bflo(p.y); v[8 * j + 3] = bfhi(p.y); v[8 * j + 4] = bflo(p.z); v[8 * j + 5] = bfhi(p.z); v[8 * j + 6] = bflo(p.w); v[8 * j + 7] = bfhi(p.w); }
; #pragma unroll
;     for (int i = 0; i < 16; ++i) s += v[i];
;     const float mean = wave_sum(s) * (1.f / 1024.f); float s2 = 0.f;
; #pragma unroll
;     for (int i = 0; i < 16; ++i) { v[i] -= mean; s2 += v[i] * v[i]; }
;     const float rstd = __builtin_amdgcn_rsqf(wave_sum(s2) * (1.f / 1024.f) + 1e-5f);
; #pragma unroll
;     for (int j = 0; j < 2; ++j) { const int c = 512 * j + 8 * lane; const f32x4 w0 = *(const f32x4*)(w + c), w1 = *(const f32x4*)(w + c + 4), b0 = *(const f32x4*)(bb + c), b1 = *(const f32x4*)(bb + c + 4);
;         f32x4 y0, y1;
; #pragma unroll
;         for (int i = 0; i < 4; ++i) { y0[i] = v[8 * j + i] * rstd * w0[i] + b0[i]; y1[i] = v[8 * j + 4 + i] * rstd * w1[i] + b1[i]; }
;         if (F32OUT) { *(f32x4*)((float*)o + c) = y0; *(f32x4*)((float*)o + c + 4) = y1; }
;         else *(u32x4*)((bf16_t*)o + c) = pack8(y0, y1); }
	v_pk_mul_f32 v[188:189], v[188:189], v[210:211] op_sel_hi:[1,0]
	v_pk_mul_f32 v[190:191], v[190:191], v[210:211] op_sel_hi:[1,0]
	v_pk_mul_f32 v[192:193], v[192:193], v[210:211] op_sel_hi:[1,0]
	v_pk_mul_f32 v[194:195], v[194:195], v[210:211] op_sel_hi:[1,0]
	v_pk_mul_f32 v[196:197], v[196:197], v[210:211] op_sel_hi:[1,0]
	v_pk_mul_f32 v[198:199], v[198:199], v[210:211] op_sel_hi:[1,0]
	v_pk_fma_f32 v[200:201], v[130:131], v[184:185], v[146:147]
	v_pk_fma_f32 v[202:203], v[132:133], v[186:187], v[148:149]
	v_pk_fma_f32 v[204:205], v[134:135], v[188:189], v[150:151]
	v_pk_fma_f32 v[206:207], v[136:137], v[190:191], v[152:153]
	global_store_dwordx4 v6, v[200:203], s[36:37]
	global_store_dwordx4 v6, v[204:207], s[36:37] offset:16
	v_pk_fma_f32 v[212:213], v[138:139], v[192:193], v[154:155]
	v_pk_fma_f32 v[214:215], v[140:141], v[194:195], v[156:157]
	v_pk_fma_f32 v[216:217], v[142:143], v[196:197], v[158:159]
	v_pk_fma_f32 v[218:219], v[144:145], v[198:199], v[160:161]
	global_store_dwordx4 v6, v[212:215], s[36:37] offset:2048
	global_store_dwordx4 v6, v[216:219], s[36:37] offset:2064
	s_add_i32 s27, s27, s31
	s_min_i32 s32, s27, 0x7a7f
	s_add_i32 s33, s32, 0x580
	s_cmp_lt_i32 s32, 0x1e80
	s_cselect_b32 s33, s32, s33
	s_mul_hi_i32 s35, s33, 0x3200
	s_mul_i32 s34, s33, 0x3200
	s_add_u32 s34, s48, s34
	s_addc_u32 s35, s49, s35
	global_load_dwordx4 v[170:173], v220, s[34:35]
	global_load_dwordx4 v[174:177], v220, s[34:35] offset:1024
	s_cmp_gt_i32 s28, 0x7a7f
	s_cbranch_scc1 .Lp11ln_done
	s_waitcnt vmcnt(18)
	v_lshlrev_b32_e32 v184, 16, v222
	v_and_b32_e32 v185, 0xffff0000, v222
	v_lshlrev_b32_e32 v186, 16, v223
	v_and_b32_e32 v187, 0xffff0000, v223
	v_lshlrev_b32_e32 v188, 16, v224
	v_and_b32_e32 v189, 0xffff0000, v224
	v_lshlrev_b32_e32 v190, 16, v225
	v_and_b32_e32 v191, 0xffff0000, v225
	v_lshlrev_b32_e32 v192, 16, v226
	v_and_b32_e32 v193, 0xffff0000, v226
	v_lshlrev_b32_e32 v194, 16, v227
	v_and_b32_e32 v195, 0xffff0000, v227
	v_lshlrev_b32_e32 v196, 16, v228
	v_and_b32_e32 v197, 0xffff0000, v228
	v_lshlrev_b32_e32 v198, 16, v229
	v_and_b32_e32 v199, 0xffff0000, v229
	v_pk_add_f32 v[200:201], v[184:185], v[186:187]
	v_pk_add_f32 v[202:203], v[188:189], v[190:191]
	v_pk_add_f32 v[204:205], v[192:193], v[194:195]
	v_pk_add_f32 v[206:207], v[196:197], v[198:199]
	v_pk_add_f32 v[200:201], v[200:201], v[202:203]
	v_pk_add_f32 v[204:205], v[204:205], v[206:207]
	v_pk_add_f32 v[200:201], v[200:201], v[204:205]
	s_nop 0
	v_add_f32_e32 v208, v200, v201
	s_nop 1
	v_add_f32_dpp v208, v208, v208 quad_perm:[1,0,3,2] row_mask:0xf bank_mask:0xf
	s_nop 1
	v_add_f32_dpp v208, v208, v208 quad_perm:[2,3,0,1] row_mask:0xf bank_mask:0xf
	s_nop 1
	v_add_f32_dpp v208, v208, v208 row_half_mirror row_mask:0xf bank_mask:0xf
	s_nop 1
	v_add_f32_dpp v208, v208, v208 row_mirror row_mask:0xf bank_mask:0xf
	s_nop 1
	v_add_f32_dpp v208, v208, v208 row_bcast:15 row_mask:0xa bank_mask:0xf
	s_nop 1
	v_add_f32_dpp v208, v208, v208 row_bcast:31 row_mask:0xc bank_mask:0xf
	s_nop 1
	v_readlane_b32 s30, v208, 63
	s_nop 1
	v_mov_b32_e32 v210, s30
	v_mul_f32_e32 v210, 0xba800000, v210
	v_pk_add_f32 v[184:185], v[184:185], v[210:211] op_sel_hi:[1,0]
	v_pk_add_f32 v[186:187], v[186:187], v[210:211] op_sel_hi:[1,0]
	v_pk_add_f32 v[188:189], v[188:189], v[210:211] op_sel_hi:[1,0]
	v_pk_add_f32 v[190:191], v[190:191], v[210:211] op_sel_hi:[1,0]
	v_pk_add_f32 v[192:193], v[192:193], v[210:211] op_sel_hi:[1,0]
	v_pk_add_f32 v[194:195], v[194:195], v[210:211] op_sel_hi:[1,0]
	v_pk_add_f32 v[196:197], v[196:197], v[210:211] op_sel_hi:[1,0]
	v_pk_add_f32 v[198:199], v[198:199], v[210:211] op_sel_hi:[1,0]
	v_pk_mul_f32 v[200:201], v[184:185], v[184:185]
	v_pk_mul_f32 v[202:203], v[192:193], v[192:193]
	v_pk_fma_f32 v[200:201], v[186:187], v[186:187], v[200:201]
	v_pk_fma_f32 v[202:203], v[194:195], v[194:195], v[202:203]
	v_pk_fma_f32 v[200:201], v[188:189], v[188:189], v[200:201]
	v_pk_fma_f32 v[202:203], v[196:197], v[196:197], v[202:203]
	v_pk_fma_f32 v[200:201], v[190:191], v[190:191], v[200:201]
	v_pk_fma_f32 v[202:203], v[198:199], v[198:199], v[202:203]
	v_pk_add_f32 v[200:201], v[200:201], v[202:203]
	s_nop 0
	v_add_f32_e32 v208, v200, v201
	s_nop 1
	v_add_f32_dpp v208, v208, v208 quad_perm:[1,0,3,2] row_mask:0xf bank_mask:0xf
	s_nop 1
	v_add_f32_dpp v208, v208, v208 quad_perm:[2,3,0,1] row_mask:0xf bank_mask:0xf
	s_nop 1
	v_add_f32_dpp v208, v208, v208 row_half_mirror row_mask:0xf bank_mask:0xf
	s_nop 1
	v_add_f32_dpp v208, v208, v208 row_mirror row_mask:0xf bank_mask:0xf
	s_nop 1
	v_add_f32_dpp v208, v208, v208 row_bcast:15 row_mask:0xa bank_mask:0xf
	s_nop 1
	v_add_f32_dpp v208, v208, v208 row_bcast:31 row_mask:0xc bank_mask:0xf
	s_nop 1
	v_readlane_b32 s30, v208, 63
	s_nop 1
	v_mov_b32_e32 v210, s30
	v_fmamk_f32 v210, v210, 0x3a800000, v13
	v_rsq_f32_e32 v210, v210
	s_add_i32 s33, s28, 0x580
	s_cmp_lt_i32 s28, 0x1e80
	s_cselect_b32 s33, s28, s33
	s_mov_b32 s36, s33
	s_mov_b32 s37, 0
	s_lshl_b64 s[36:37], s[36:37], 12
	s_add_u32 s36, s42, s36
	s_addc_u32 s37, s43, s37
	v_pk_mul_f32 v[184:185], v[184:185], v[210:211] op_sel_hi:[1,0]
	v_pk_mul_f32 v[186:187], v[186:187], v[210:211] op_sel_hi:[1,0]
	v_pk_mul_f32 v[188:189], v[188:189], v[210:211] op_sel_hi:[1,0]
	v_pk_mul_f32 v[190:191], v[190:191], v[210:211] op_sel_hi:[1,0]
	v_pk_mul_f32 v[192:193], v[192:193], v[210:211] op_sel_hi:[1,0]
	v_pk_mul_f32 v[194:195], v[194:195], v[210:211] op_sel_hi:[1,0]
	v_pk_mul_f32 v[196:197], v[196:197], v[210:211] op_sel_hi:[1,0]
	v_pk_mul_f32 v[198:199], v[198:199], v[210:211] op_sel_hi:[1,0]
	v_pk_fma_f32 v[200:201], v[130:131], v[184:185], v[146:147]
	v_pk_fma_f32 v[202:203], v[132:133], v[186:187], v[148:149]
	v_pk_fma_f32 v[204:205], v[134:135], v[188:189], v[150:151]
	v_pk_fma_f32 v[206:207], v[136:137], v[190:191], v[152:153]
	global_store_dwordx4 v6, v[200:203], s[36:37]
	global_store_dwordx4 v6, v[204:207], s[36:37] offset:16
	v_pk_fma_f32 v[212:213], v[138:139], v[192:193], v[154:155]
	v_pk_fma_f32 v[214:215], v[140:141], v[194:195], v[156:157]
	v_pk_fma_f32 v[216:217], v[142:143], v[196:197], v[158:159]
	v_pk_fma_f32 v[218:219], v[144:145], v[198:199], v[160:161]
	global_store_dwordx4 v6, v[212:215], s[36:37] offset:2048
	global_store_dwordx4 v6, v[216:219], s[36:37] offset:2064
	s_add_i32 s28, s28, s31
	s_min_i32 s32, s28, 0x7a7f
	s_add_i32 s33, s32, 0x580
	s_cmp_lt_i32 s32, 0x1e80
	s_cselect_b32 s33, s32, s33
	s_mul_hi_i32 s35, s33, 0x3200
	s_mul_i32 s34, s33, 0x3200
	s_add_u32 s34, s48, s34
	s_addc_u32 s35, s49, s35
	global_load_dwordx4 v[222:225], v220, s[34:35]
	global_load_dwordx4 v[226:229], v220, s[34:35] offset:1024
	s_cmp_gt_i32 s29, 0x7a7f
	s_cbranch_scc1 .Lp11ln_done
; DI float bflo(unsigned w) { return __uint_as_float(w << 16); }
; DI float bfhi(unsigned w) { return __uint_as_float(w & 0xffff0000u); }
; DI u32x4 pack8(f32x4 a, f32x4 b) { u32x4 w; w.x = pk2(a[0], a[1]); w.y = pk2(a[2], a[3]); w.z = pk2(b[0], b[1]); w.w = pk2(b[2], b[3]); return w; }
; template <bool F32OUT> DI void ln_row_bf16(const bf16_t* z, const float* w, const float* bb, void* o, int lane) {
;     float v[16]; float s = 0.f;
; #pragma unroll
;     for (int j = 0; j < 2; ++j) { const u32x4 p = *(const u32x4*)(z + 512 * j + 8 * lane);
;         v[8 * j + 0] = bflo(p.x); v[8 * j + 1] = bfhi(p.x); v[8 * j + 2] = bflo(p.y); v[8 * j + 3] = bfhi(p.y); v[8 * j + 4] = bflo(p.z); v[8 * j + 5] = bfhi(p.z); v[8 * j + 6] = bflo(p.w); v[8 * j + 7] = bfhi(p.w); }
; #pragma unroll
;     for (int i = 0; i < 16; ++i) s += v[i];
;     const float mean = wave_sum(s) * (1.f / 1024.f); float s2 = 0.f;
; #pragma unroll
;     for (int i = 0; i < 16; ++i) { v[i] -= mean; s2 += v[i] * v[i]; }
;     const float rstd = __builtin_amdgcn_rsqf(wave_sum(s2) * (1.f / 1024.f) + 1e-5f);
; #pragma unroll
;     for (int j = 0; j < 2; ++j) { const int c = 512 * j + 8 * lane; const f32x4 w0 = *(const f32x4*)(w + c), w1 = *(const f32x4*)(w + c + 4), b0 = *(const f32x4*)(bb + c), b1 = *(const f32x4*)(bb + c + 4);
;         f32x4 y0, y1;
; #pragma unroll
;         for (int i = 0; i < 4; ++i) { y0[i] = v[8 * j + i] * rstd * w0[i] + b0[i]; y1[i] = v[8 * j + 4 + i] * rstd * w1[i] + b1[i]; }
;         if (F32OUT) { *(f32x4*)((float*)o + c) = y0; *(f32x4*)((float*)o + c + 4) = y1; }
;         else *(u32x4*)((bf16_t*)o + c) = pack8(y0, y1); }
; __global__ void __launch_bounds__(512, 2) fwd_kernel(Params P) {
;     ...
;         else { for (int m = (cu - 32) * 8 + wave; m < MP; m += (G - 32) * 8) if (m < 7808 || m >= 9216) ln_row_bf16<true>(PROJ + (size_t)m * NPJ + C_Z, P.in[I_LN2W], P.in[I_LN2B], P.out + O_YP + (size_t)m * 1024, lane); }
	s_waitcnt vmcnt(18)
	v_lshlrev_b32_e32 v184, 16, v230
	v_and_b32_e32 v185, 0xffff0000, v230
	v_lshlrev_b32_e32 v186, 16, v231
	v_and_b32_e32 v187, 0xffff0000, v231
	v_lshlrev_b32_e32 v188, 16, v232
	v_and_b32_e32 v189, 0xffff0000, v232
	v_lshlrev_b32_e32 v190, 16, v233
	v_and_b32_e32 v191, 0xffff0000, v233
	v_lshlrev_b32_e32 v192, 16, v234
	v_and_b32_e32 v193, 0xffff0000, v234
	v_lshlrev_b32_e32 v194, 16, v235
	v_and_b32_e32 v195, 0xffff0000, v235
	v_lshlrev_b32_e32 v196, 16, v236
	v_and_b32_e32 v197, 0xffff0000, v236
	v_lshlrev_b32_e32 v198, 16, v237
	v_and_b32_e32 v199, 0xffff0000, v237
	v_pk_add_f32 v[200:201], v[184:185], v[186:187]
	v_pk_add_f32 v[202:203], v[188:189], v[190:191]
	v_pk_add_f32 v[204:205], v[192:193], v[194:195]
	v_pk_add_f32 v[206:207], v[196:197], v[198:199]
	v_pk_add_f32 v[200:201], v[200:201], v[202:203]
	v_pk_add_f32 v[204:205], v[204:205], v[206:207]
	v_pk_add_f32 v[200:201], v[200:201], v[204:205]
	s_nop 0
	v_add_f32_e32 v208, v200, v201
	s_nop 1
	v_add_f32_dpp v208, v208, v208 quad_perm:[1,0,3,2] row_mask:0xf bank_mask:0xf
	s_nop 1
	v_add_f32_dpp v208, v208, v208 quad_perm:[2,3,0,1] row_mask:0xf bank_mask:0xf
	s_nop 1
	v_add_f32_dpp v208, v208, v208 row_half_mirror row_mask:0xf bank_mask:0xf
	s_nop 1
	v_add_f32_dpp v208, v208, v208 row_mirror row_mask:0xf bank_mask:0xf
	s_nop 1
	v_add_f32_dpp v208, v208, v208 row_bcast:15 row_mask:0xa bank_mask:0xf
	s_nop 1
	v_add_f32_dpp v208, v208, v208 row_bcast:31 row_mask:0xc bank_mask:0xf
	s_nop 1
	v_readlane_b32 s30, v208, 63
	s_nop 1
	v_mov_b32_e32 v210, s30
	v_mul_f32_e32 v210, 0xba800000, v210
	v_pk_add_f32 v[184:185], v[184:185], v[210:211] op_sel_hi:[1,0]
	v_pk_add_f32 v[186:187], v[186:187], v[210:211] op_sel_hi:[1,0]
	v_pk_add_f32 v[188:189], v[188:189], v[210:211] op_sel_hi:[1,0]
	v_pk_add_f32 v[190:191], v[190:191], v[210:211] op_sel_hi:[1,0]
	v_pk_add_f32 v[192:193], v[192:193], v[210:211] op_sel_hi:[1,0]
	v_pk_add_f32 v[194:195], v[194:195], v[210:211] op_sel_hi:[1,0]
	v_pk_add_f32 v[196:197], v[196:197], v[210:211] op_sel_hi:[1,0]
	v_pk_add_f32 v[198:199], v[198:199], v[210:211] op_sel_hi:[1,0]
	v_pk_mul_f32 v[200:201], v[184:185], v[184:185]
	v_pk_mul_f32 v[202:203], v[192:193], v[192:193]
	v_pk_fma_f32 v[200:201], v[186:187], v[186:187], v[200:201]
	v_pk_fma_f32 v[202:203], v[194:195], v[194:195], v[202:203]
	v_pk_fma_f32 v[200:201], v[188:189], v[188:189], v[200:201]
	v_pk_fma_f32 v[202:203], v[196:197], v[196:197], v[202:203]
	v_pk_fma_f32 v[200:201], v[190:191], v[190:191], v[200:201]
	v_pk_fma_f32 v[202:203], v[198:199], v[198:199], v[202:203]
	v_pk_add_f32 v[200:201], v[200:201], v[202:203]
	s_nop 0
	v_add_f32_e32 v208, v200, v201
	s_nop 1
	v_add_f32_dpp v208, v208, v208 quad_perm:[1,0,3,2] row_mask:0xf bank_mask:0xf
	s_nop 1
	v_add_f32_dpp v208, v208, v208 quad_perm:[2,3,0,1] row_mask:0xf bank_mask:0xf
	s_nop 1
	v_add_f32_dpp v208, v208, v208 row_half_mirror row_mask:0xf bank_mask:0xf
	s_nop 1
	v_add_f32_dpp v208, v208, v208 row_mirror row_mask:0xf bank_mask:0xf
	s_nop 1
	v_add_f32_dpp v208, v208, v208 row_bcast:15 row_mask:0xa bank_mask:0xf
	s_nop 1
	v_add_f32_dpp v208, v208, v208 row_bcast:31 row_mask:0xc bank_mask:0xf
	s_nop 1
	v_readlane_b32 s30, v208, 63
	s_nop 1
	v_mov_b32_e32 v210, s30
	v_fmamk_f32 v210, v210, 0x3a800000, v13
	v_rsq_f32_e32 v210, v210
	s_add_i32 s33, s29, 0x580
	s_cmp_lt_i32 s29, 0x1e80
	s_cselect_b32 s33, s29, s33
	s_mov_b32 s36, s33
	s_mov_b32 s37, 0
	s_lshl_b64 s[36:37], s[36:37], 12
	s_add_u32 s36, s42, s36
	s_addc_u32 s37, s43, s37
	v_pk_mul_f32 v[184:185], v[184:185], v[210:211] op_sel_hi:[1,0]
	v_pk_mul_f32 v[186:187], v[186:187], v[210:211] op_sel_hi:[1,0]
	v_pk_mul_f32 v[188:189], v[188:189], v[210:211] op_sel_hi:[1,0]
	v_pk_mul_f32 v[190:191], v[190:191], v[210:211] op_sel_hi:[1,0]
	v_pk_mul_f32 v[192:193], v[192:193], v[210:211] op_sel_hi:[1,0]
	v_pk_mul_f32 v[194:195], v[194:195], v[210:211] op_sel_hi:[1,0]
	v_pk_mul_f32 v[196:197], v[196:197], v[210:211] op_sel_hi:[1,0]
	v_pk_mul_f32 v[198:199], v[198:199], v[210:211] op_sel_hi:[1,0]
	v_pk_fma_f32 v[200:201], v[130:131], v[184:185], v[146:147]
	v_pk_fma_f32 v[202:203], v[132:133], v[186:187], v[148:149]
	v_pk_fma_f32 v[204:205], v[134:135], v[188:189], v[150:151]
	v_pk_fma_f32 v[206:207], v[136:137], v[190:191], v[152:153]
	global_store_dwordx4 v6, v[200:203], s[36:37]
	global_store_dwordx4 v6, v[204:207], s[36:37] offset:16
	v_pk_fma_f32 v[212:213], v[138:139], v[192:193], v[154:155]
	v_pk_fma_f32 v[214:215], v[140:141], v[194:195], v[156:157]
	v_pk_fma_f32 v[216:217], v[142:143], v[196:197], v[158:159]
	v_pk_fma_f32 v[218:219], v[144:145], v[198:199], v[160:161]
	global_store_dwordx4 v6, v[212:215], s[36:37] offset:2048
	global_store_dwordx4 v6, v[216:219], s[36:37] offset:2064
	s_add_i32 s29, s29, s31
	s_min_i32 s32, s29, 0x7a7f
	s_add_i32 s33, s32, 0x580
	s_cmp_lt_i32 s32, 0x1e80
	s_cselect_b32 s33, s32, s33
	s_mul_hi_i32 s35, s33, 0x3200
	s_mul_i32 s34, s33, 0x3200
	s_add_u32 s34, s48, s34
	s_addc_u32 s35, s49, s35
	global_load_dwordx4 v[230:233], v220, s[34:35]
	global_load_dwordx4 v[234:237], v220, s[34:35] offset:1024
	s_branch .Lp11ln_loop
.Lp11ln_done:
	s_waitcnt vmcnt(0)
.LBB0_1690:
	s_mov_b64 s[8:9], 0
